# mLSTM: K-image LDS-DMA pieces of waves 0-3 issued by their partner waves 4-7 (per-lane address delta), waves 0-3 only load their q fragments after barrier 1
# baseline (speedup 1.0000x reference)
; #define LAS __attribute__((address_space(3)))
; #define MLK_ISSUE(chunk_off_elems, buf) do { const char* kg_ = (const char*)(k + (chunk_off_elems)); _Pragma("unroll") for (int i_ = 0; i_ < 4; ++i_) \
;             __builtin_amdgcn_global_load_lds((const unsigned*)(kg_ + kvoff + (size_t)i_ * 16 * DM * 2), (LAS unsigned*)(shm + (buf) * 32768 + (i_ * 8 + wid) * 1024), 16, 0, 0); } while (0)
; #define gpart ((float*)S7(IPRE_OFF))
; template <int SKIP>
; DEV void mlstm_phase(LAS char* shm, const bf16_t* q, const bf16_t* k, const bf16_t* v, const float* gpart, const float* b_ig, const float* b_fg, bf16_t* hc, const bool pre) {
;     ...
;         const int vs = (item >> 3) & 7, bh = (item & 7) + 8 * (item >> 6), h = bh & 3, b = bh >> 2;
;         const size_t cb0 = ((size_t)(b * SEQ)) * DM + h * DH;
;         __syncthreads();
;         unsigned kvoff; { const int rw = 2 * wid + (lane >> 5); kvoff = (unsigned)(rw * DM + (((lane & 31) ^ rw) * 8)) * 2u; asm volatile("" : "+v"(kvoff)); }
;     ...
;         MLK_ISSUE(cb0, 0);
;         bf16x8 qfr[8];
;         const bf16_t* qfb = q + ((size_t)((b * 4 + h) * 32) * 4 + (wid & 3)) * 4096 + lane * 8;
; #pragma unroll
;         for (int ks = 0; ks < 8; ++ks) qfr[ks] = *(const bf16x8*)(qfb + ks * 512);
;         uint4 vv = make_uint4(0, 0, 0, 0);
;         if (wid < 4) vv = *(const uint4*)(v + cb0 + (size_t)(tid >> 2) * DM + vs * 32 + (tid & 3) * 8);
;         for (int i = tid; i < (CB + 25344 - VT) / 4; i += 512) ((LAS unsigned*)(shm + VT))[i] = 0u;
;         if (!(pre && item == (int)blockIdx.x)) mlstm_gate_scans(shm, gpart, b_ig, b_fg, item);
;         __syncthreads();
;         if (wid == 0) *(LAS unsigned*)(shm + VT + tid * VRS + 64) = 0x3F80u;
;         const int ndt = (wid == 0 || wid == 4 || wid == 1) ? 3 : ((wid == 5 || wid == 2) ? 2 : 1);
;         const int dt0 = (wid == 0) ? 0 : (wid == 4) ? 3 : (wid == 1) ? 6 : (wid == 5) ? 9 : (wid == 2) ? 11 : (wid == 6) ? 13 : (wid == 3) ? 14 : 15;
;         f32x4 cacc[3][3];
; #pragma unroll
;         for (int i = 0; i < 3; ++i)
; #pragma unroll
;             for (int vt = 0; vt < 3; ++vt) cacc[i][vt] = (f32x4){0.f, 0.f, 0.f, 0.f};
;         float m_prev = 0.f;
.LBB0_634:
	v_and_b32_e32 v252, 8, v214
	v_lshlrev_b32_e32 v252, 5, v252
	v_add_u32_e32 v252, 0xffffbf80, v252
	v_ashrrev_i32_e32 v253, 31, v252
	s_bfe_u32 s0, s79, 0x10002
	s_lshl_b32 s1, s0, 11
	s_lshl_b32 s40, s0, 2
	s_and_b32 s0, s57, 7
	s_lshl_b32 s41, s0, 6
	s_lshl_b32 s0, s38, 1
	s_and_b32 s39, s78, 3
	v_bitop3_b32 v0, s0, v189, v188 bitop3:0x36
	s_lshl_b32 s74, s39, 9
	v_lshlrev_b32_e32 v167, 4, v0
	v_bitop3_b32 v0, s0, v191, v188 bitop3:0x36
	v_lshlrev_b32_e32 v220, 4, v0
	s_cmp_gt_u32 s36, 1
	v_add_u32_e32 v0, s0, v196
	s_cselect_b64 s[34:35], -1, 0
	v_xor_b32_e32 v1, v0, v189
	v_xor_b32_e32 v0, v0, v191
	s_cmp_eq_u32 s36, 3
	v_lshlrev_b32_e32 v222, 4, v0
	s_cselect_b64 s[36:37], -1, 0
	v_add_u32_e32 v0, s0, v197
	s_lshl_b32 s0, s45, 9
	s_and_b32 s0, s0, 0xfffff000
	s_or_b32 s0, s0, s1
	s_ashr_i32 s1, s0, 31
	s_lshl_b64 s[28:29], s[0:1], 11
	s_add_u32 s30, s55, s28
	s_addc_u32 s31, s56, s29
	v_lshl_add_u64 v[168:169], s[30:31], 0, v[2:3]
	s_add_i32 s30, s52, s40
	v_lshlrev_b32_e32 v221, 4, v1
	v_xor_b32_e32 v1, v0, v189
	v_xor_b32_e32 v0, v0, v191
	s_add_i32 s30, s30, s39
	v_lshlrev_b32_e32 v223, 4, v1
	v_lshlrev_b32_e32 v224, 4, v0
	s_lshl_b32 s30, s30, 5
	v_lshl_add_u64 v[0:1], v[158:159], 0, s[0:1]
	v_lshl_add_u32 v54, s38, 5, v192
	s_ashr_i32 s31, s30, 31
	v_lshlrev_b64 v[0:1], 11, v[0:1]
	v_mov_b32_e32 v4, v3
	v_mov_b32_e32 v5, v3
	s_lshl_b64 s[30:31], s[30:31], 15
	s_or_b32 s28, s28, s41
	v_or_b32_e32 v0, s41, v0
	v_mov_b32_e32 v2, v3
	v_add_u32_e32 v225, v54, v178
	v_add_u32_e32 v226, v54, v195
	v_mov_b64_e32 v[64:65], v[4:5]
	v_mov_b64_e32 v[68:69], v[4:5]
	v_mov_b64_e32 v[56:57], v[4:5]
	v_mov_b64_e32 v[72:73], v[4:5]
	v_mov_b64_e32 v[76:77], v[4:5]
	v_mov_b64_e32 v[60:61], v[4:5]
	v_lshl_add_u64 v[170:171], v[154:155], 0, s[30:31]
	v_lshl_add_u64 v[172:173], v[162:163], 0, s[28:29]
	v_lshl_add_u64 v[174:175], v[164:165], 0, v[0:1]
	s_mov_b32 s28, 0
	s_movk_i32 s40, 0xe000
	s_mov_b64 s[38:39], 0
	v_mov_b32_e32 v42, 0
	v_mov_b32_e32 v43, 0
	v_mov_b32_e32 v44, 0
	v_mov_b32_e32 v45, 0
	v_mov_b32_e32 v46, 0
	v_mov_b32_e32 v47, 0
	v_mov_b32_e32 v48, 0
	v_mov_b32_e32 v49, 0
	v_mov_b32_e32 v50, 0
	v_mov_b32_e32 v51, 0
	v_mov_b32_e32 v52, 0
	v_mov_b32_e32 v53, 0
	s_mov_b32 s41, s54
	v_mov_b64_e32 v[62:63], v[2:3]
	v_mov_b64_e32 v[66:67], v[2:3]
	v_mov_b64_e32 v[54:55], v[2:3]
	v_mov_b64_e32 v[70:71], v[2:3]
	v_mov_b64_e32 v[74:75], v[2:3]
	v_mov_b64_e32 v[58:59], v[2:3]
	s_branch .LBB0_636

; #define MLK_ISSUE(chunk_off_elems, buf) do { const char* kg_ = (const char*)(k + (chunk_off_elems)); _Pragma("unroll") for (int i_ = 0; i_ < 4; ++i_) \
;             __builtin_amdgcn_global_load_lds((const unsigned*)(kg_ + kvoff + (size_t)i_ * 16 * DM * 2), (LAS unsigned*)(shm + (buf) * 32768 + (i_ * 8 + wid) * 1024), 16, 0, 0); } while (0)
; template <int SKIP>
; DEV void mlstm_phase(LAS char* shm, const bf16_t* q, const bf16_t* k, const bf16_t* v, const float* gpart, const float* b_ig, const float* b_fg, bf16_t* hc, const bool pre) {
;     ...
;             if (j + 1 < SEQ / CHUNK) {
;                 const size_t cn = cb + (size_t)CHUNK * DM;
;                 MLK_ISSUE(cn, (j + 1) & 1);
; #pragma unroll
;                 for (int ks = 0; ks < 8; ++ks) qnx[ks] = *(const bf16x8*)(qfb + (size_t)(j + 1) * 16384 + ks * 512);
;                 if (wid < 4) vv = *(const uint4*)(v + cn + (size_t)(tid >> 2) * DM + vs * 32 + (tid & 3) * 8);
;             }
.LBB0_641:
	v_lshl_add_u64 v[0:1], v[168:169], 0, s[74:75]
	s_mov_b64 s[0:1], 0x2032000
	v_lshl_add_u64 v[4:5], v[0:1], 0, s[0:1]
	s_add_i32 s0, s38, 0x8000
	s_and_b32 s0, s0, 0x8000
	s_add_i32 s29, s65, s0
	s_mov_b32 m0, s29
	s_mov_b64 s[0:1], 0x203a000
	global_load_lds_dwordx4 v[4:5], off
	v_lshl_add_u64 v[4:5], v[0:1], 0, s[0:1]
	s_add_i32 m0, s29, 0x2000
	s_mov_b64 s[0:1], 0x2042000
	global_load_lds_dwordx4 v[4:5], off
	v_lshl_add_u64 v[4:5], v[0:1], 0, s[0:1]
	s_add_i32 m0, s29, 0x4000
	s_mov_b64 s[0:1], 0x204a000
	global_load_lds_dwordx4 v[4:5], off
	v_lshl_add_u64 v[0:1], v[0:1], 0, s[0:1]
	s_add_i32 m0, s29, 0x6000
	s_mov_b32 s0, 0xc074000
	global_load_lds_dwordx4 v[0:1], off
	v_lshl_add_u64 v[250:251], v[168:169], 0, s[74:75]
	v_lshl_add_u64 v[250:251], v[250:251], 0, v[252:253]
	s_mov_b64 s[0:1], 0x2032000
	v_lshl_add_u64 v[4:5], v[250:251], 0, s[0:1]
	s_add_i32 m0, s29, 0xfffff000
	s_mov_b64 s[0:1], 0x203a000
	global_load_lds_dwordx4 v[4:5], off
	v_lshl_add_u64 v[4:5], v[250:251], 0, s[0:1]
	s_add_i32 m0, s29, 0x1000
	s_mov_b64 s[0:1], 0x2042000
	global_load_lds_dwordx4 v[4:5], off
	v_lshl_add_u64 v[4:5], v[250:251], 0, s[0:1]
	s_add_i32 m0, s29, 0x3000
	s_mov_b64 s[0:1], 0x204a000
	global_load_lds_dwordx4 v[4:5], off
	v_lshl_add_u64 v[4:5], v[250:251], 0, s[0:1]
	s_add_i32 m0, s29, 0x5000
	s_mov_b32 s0, 0xc074000
	global_load_lds_dwordx4 v[4:5], off
	v_lshl_add_u64 v[0:1], v[170:171], 0, s[38:39]
	v_add_co_u32_e32 v4, vcc, s0, v0
	s_nop 1
	v_addc_co_u32_e32 v5, vcc, 0, v1, vcc
	v_add_co_u32_e32 v0, vcc, 0xc075000, v0
	global_load_dwordx4 v[98:101], v[4:5], off
	global_load_dwordx4 v[90:93], v[4:5], off offset:1024
	global_load_dwordx4 v[82:85], v[4:5], off offset:2048
	global_load_dwordx4 v[78:81], v[4:5], off offset:3072
	v_addc_co_u32_e32 v1, vcc, 0, v1, vcc
	global_load_dwordx4 v[106:109], v[0:1], off
	global_load_dwordx4 v[102:105], v[0:1], off offset:1024
	global_load_dwordx4 v[94:97], v[0:1], off offset:2048
	global_load_dwordx4 v[86:89], v[0:1], off offset:3072
	s_and_b64 vcc, exec, s[26:27]
	s_cbranch_vccnz .LBB0_650
	v_lshl_add_u64 v[0:1], v[174:175], 0, s[74:75]
	v_add_co_u32_e32 v0, vcc, 0xa07a000, v0
	s_nop 1
	v_addc_co_u32_e32 v1, vcc, 0, v1, vcc
	global_load_dwordx4 v[6:9], v[0:1], off
	s_branch .LBB0_650

; #define MLK_ISSUE(chunk_off_elems, buf) do { const char* kg_ = (const char*)(k + (chunk_off_elems)); _Pragma("unroll") for (int i_ = 0; i_ < 4; ++i_) \
;             __builtin_amdgcn_global_load_lds((const unsigned*)(kg_ + kvoff + (size_t)i_ * 16 * DM * 2), (LAS unsigned*)(shm + (buf) * 32768 + (i_ * 8 + wid) * 1024), 16, 0, 0); } while (0)
; template <int SKIP>
; DEV void mlstm_phase(LAS char* shm, const bf16_t* q, const bf16_t* k, const bf16_t* v, const float* gpart, const float* b_ig, const float* b_fg, bf16_t* hc, const bool pre) {
;     ...
;             if (j + 1 < SEQ / CHUNK) {
;                 const size_t cn = cb + (size_t)CHUNK * DM;
;                 MLK_ISSUE(cn, (j + 1) & 1);
; #pragma unroll
;                 for (int ks = 0; ks < 8; ++ks) qnx[ks] = *(const bf16x8*)(qfb + (size_t)(j + 1) * 16384 + ks * 512);
;                 if (wid < 4) vv = *(const uint4*)(v + cn + (size_t)(tid >> 2) * DM + vs * 32 + (tid & 3) * 8);
;             }
;             asm volatile("s_waitcnt lgkmcnt(0)\n\ts_barrier" ::: "memory");
.LBB0_650:
	s_waitcnt lgkmcnt(0)
	s_barrier
	s_and_b64 vcc, exec, s[84:85]
	s_cbranch_vccnz .Lpf0_done
	s_cmpk_eq_i32 s40, 0xff00
	s_cbranch_scc1 .Lpf0_skip
	s_mov_b32 s0, 0xc074000
	v_lshl_add_u64 v[0:1], v[170:171], 0, s[38:39]
	v_add_co_u32_e32 v4, vcc, s0, v0
	s_nop 1
	v_addc_co_u32_e32 v5, vcc, 0, v1, vcc
	v_add_co_u32_e32 v0, vcc, 0xc075000, v0
	global_load_dwordx4 v[98:101], v[4:5], off
	global_load_dwordx4 v[90:93], v[4:5], off offset:1024
	global_load_dwordx4 v[82:85], v[4:5], off offset:2048
	global_load_dwordx4 v[78:81], v[4:5], off offset:3072
	v_addc_co_u32_e32 v1, vcc, 0, v1, vcc
	global_load_dwordx4 v[106:109], v[0:1], off
	global_load_dwordx4 v[102:105], v[0:1], off offset:1024
	global_load_dwordx4 v[94:97], v[0:1], off offset:2048
	global_load_dwordx4 v[86:89], v[0:1], off offset:3072
	v_lshl_add_u64 v[0:1], v[174:175], 0, s[74:75]
	v_add_co_u32_e32 v0, vcc, 0xa07a000, v0
	s_nop 1
	v_addc_co_u32_e32 v1, vcc, 0, v1, vcc
	global_load_dwordx4 v[6:9], v[0:1], off

; #define LAS __attribute__((address_space(3)))
; #define MLK_ISSUE(chunk_off_elems, buf) do { const char* kg_ = (const char*)(k + (chunk_off_elems)); _Pragma("unroll") for (int i_ = 0; i_ < 4; ++i_) \
;             __builtin_amdgcn_global_load_lds((const unsigned*)(kg_ + kvoff + (size_t)i_ * 16 * DM * 2), (LAS unsigned*)(shm + (buf) * 32768 + (i_ * 8 + wid) * 1024), 16, 0, 0); } while (0)
; #define gpart ((float*)S7(IPRE_OFF))
; template <int SKIP>
; DEV void mlstm_phase(LAS char* shm, const bf16_t* q, const bf16_t* k, const bf16_t* v, const float* gpart, const float* b_ig, const float* b_fg, bf16_t* hc, const bool pre) {
;     ...
;         const int vs = (item >> 3) & 7, bh = (item & 7) + 8 * (item >> 6), h = bh & 3, b = bh >> 2;
;         const size_t cb0 = ((size_t)(b * SEQ)) * DM + h * DH;
;         __syncthreads();
;         unsigned kvoff; { const int rw = 2 * wid + (lane >> 5); kvoff = (unsigned)(rw * DM + (((lane & 31) ^ rw) * 8)) * 2u; asm volatile("" : "+v"(kvoff)); }
;     ...
;         MLK_ISSUE(cb0, 0);
;         bf16x8 qfr[8];
;         const bf16_t* qfb = q + ((size_t)((b * 4 + h) * 32) * 4 + (wid & 3)) * 4096 + lane * 8;
; #pragma unroll
;         for (int ks = 0; ks < 8; ++ks) qfr[ks] = *(const bf16x8*)(qfb + ks * 512);
;         uint4 vv = make_uint4(0, 0, 0, 0);
;         if (wid < 4) vv = *(const uint4*)(v + cb0 + (size_t)(tid >> 2) * DM + vs * 32 + (tid & 3) * 8);
;         for (int i = tid; i < (CB + 25344 - VT) / 4; i += 512) ((LAS unsigned*)(shm + VT))[i] = 0u;
;         if (!(pre && item == (int)blockIdx.x)) mlstm_gate_scans(shm, gpart, b_ig, b_fg, item);
;         __syncthreads();
;         if (wid == 0) *(LAS unsigned*)(shm + VT + tid * VRS + 64) = 0x3F80u;
;         const int ndt = (wid == 0 || wid == 4 || wid == 1) ? 3 : ((wid == 5 || wid == 2) ? 2 : 1);
;         const int dt0 = (wid == 0) ? 0 : (wid == 4) ? 3 : (wid == 1) ? 6 : (wid == 5) ? 9 : (wid == 2) ? 11 : (wid == 6) ? 13 : (wid == 3) ? 14 : 15;
;         f32x4 cacc[3][3];
; #pragma unroll
;         for (int i = 0; i < 3; ++i)
; #pragma unroll
;             for (int vt = 0; vt < 3; ++vt) cacc[i][vt] = (f32x4){0.f, 0.f, 0.f, 0.f};
;         float m_prev = 0.f;
.LBB0_1485:
	v_and_b32_e32 v252, 8, v214
	v_lshlrev_b32_e32 v252, 5, v252
	v_add_u32_e32 v252, 0xffffbf80, v252
	v_ashrrev_i32_e32 v253, 31, v252
	s_bfe_u32 s0, s91, 0x10002
	s_lshl_b32 s1, s0, 11
	s_lshl_b32 s40, s0, 2
	s_and_b32 s0, s77, 7
	s_lshl_b32 s41, s0, 6
	s_lshl_b32 s0, s38, 1
	s_and_b32 s39, s79, 3
	v_bitop3_b32 v0, s0, v189, v188 bitop3:0x36
	s_lshl_b32 s64, s39, 9
	v_lshlrev_b32_e32 v167, 4, v0
	v_bitop3_b32 v0, s0, v191, v188 bitop3:0x36
	v_lshlrev_b32_e32 v220, 4, v0
	s_cmp_gt_u32 s36, 1
	v_add_u32_e32 v0, s0, v196
	s_cselect_b64 s[34:35], -1, 0
	v_xor_b32_e32 v1, v0, v189
	v_xor_b32_e32 v0, v0, v191
	s_cmp_eq_u32 s36, 3
	v_lshlrev_b32_e32 v222, 4, v0
	s_cselect_b64 s[36:37], -1, 0
	v_add_u32_e32 v0, s0, v197
	s_lshl_b32 s0, s76, 9
	s_and_b32 s0, s0, 0xfffff000
	s_or_b32 s0, s0, s1
	s_ashr_i32 s1, s0, 31
	s_lshl_b64 s[28:29], s[0:1], 11
	s_add_u32 s30, s53, s28
	s_addc_u32 s31, s55, s29
	v_lshl_add_u64 v[168:169], s[30:31], 0, v[2:3]
	s_add_i32 s30, s52, s40
	v_lshlrev_b32_e32 v221, 4, v1
	v_xor_b32_e32 v1, v0, v189
	v_xor_b32_e32 v0, v0, v191
	s_add_i32 s30, s30, s39
	v_lshlrev_b32_e32 v223, 4, v1
	v_lshlrev_b32_e32 v224, 4, v0
	s_lshl_b32 s30, s30, 5
	v_lshl_add_u64 v[0:1], v[158:159], 0, s[0:1]
	v_lshl_add_u32 v54, s38, 5, v192
	s_ashr_i32 s31, s30, 31
	v_lshlrev_b64 v[0:1], 11, v[0:1]
	v_mov_b32_e32 v4, v3
	v_mov_b32_e32 v5, v3
	s_lshl_b64 s[30:31], s[30:31], 15
	s_or_b32 s28, s28, s41
	v_or_b32_e32 v0, s41, v0
	v_mov_b32_e32 v2, v3
	v_add_u32_e32 v225, v54, v178
	v_add_u32_e32 v226, v54, v195
	v_mov_b64_e32 v[64:65], v[4:5]
	v_mov_b64_e32 v[68:69], v[4:5]
	v_mov_b64_e32 v[56:57], v[4:5]
	v_mov_b64_e32 v[72:73], v[4:5]
	v_mov_b64_e32 v[76:77], v[4:5]
	v_mov_b64_e32 v[60:61], v[4:5]
	v_lshl_add_u64 v[170:171], v[154:155], 0, s[30:31]
	v_lshl_add_u64 v[172:173], v[162:163], 0, s[28:29]
	v_lshl_add_u64 v[174:175], v[164:165], 0, v[0:1]
	s_mov_b32 s28, 0
	s_movk_i32 s40, 0xe000
	s_mov_b64 s[38:39], 0
	v_mov_b32_e32 v42, 0
	v_mov_b32_e32 v43, 0
	v_mov_b32_e32 v44, 0
	v_mov_b32_e32 v45, 0
	v_mov_b32_e32 v46, 0
	v_mov_b32_e32 v47, 0
	v_mov_b32_e32 v48, 0
	v_mov_b32_e32 v49, 0
	v_mov_b32_e32 v50, 0
	v_mov_b32_e32 v51, 0
	v_mov_b32_e32 v52, 0
	v_mov_b32_e32 v53, 0
	s_mov_b32 s41, s54
	v_mov_b64_e32 v[62:63], v[2:3]
	v_mov_b64_e32 v[66:67], v[2:3]
	v_mov_b64_e32 v[54:55], v[2:3]
	v_mov_b64_e32 v[70:71], v[2:3]
	v_mov_b64_e32 v[74:75], v[2:3]
	v_mov_b64_e32 v[58:59], v[2:3]
	s_branch .LBB0_1487

; #define MLK_ISSUE(chunk_off_elems, buf) do { const char* kg_ = (const char*)(k + (chunk_off_elems)); _Pragma("unroll") for (int i_ = 0; i_ < 4; ++i_) \
;             __builtin_amdgcn_global_load_lds((const unsigned*)(kg_ + kvoff + (size_t)i_ * 16 * DM * 2), (LAS unsigned*)(shm + (buf) * 32768 + (i_ * 8 + wid) * 1024), 16, 0, 0); } while (0)
; template <int SKIP>
; DEV void mlstm_phase(LAS char* shm, const bf16_t* q, const bf16_t* k, const bf16_t* v, const float* gpart, const float* b_ig, const float* b_fg, bf16_t* hc, const bool pre) {
;     ...
;             if (j + 1 < SEQ / CHUNK) {
;                 const size_t cn = cb + (size_t)CHUNK * DM;
;                 MLK_ISSUE(cn, (j + 1) & 1);
; #pragma unroll
;                 for (int ks = 0; ks < 8; ++ks) qnx[ks] = *(const bf16x8*)(qfb + (size_t)(j + 1) * 16384 + ks * 512);
;                 if (wid < 4) vv = *(const uint4*)(v + cn + (size_t)(tid >> 2) * DM + vs * 32 + (tid & 3) * 8);
;             }
.LBB0_1492:
	v_lshl_add_u64 v[0:1], v[168:169], 0, s[64:65]
	s_mov_b64 s[0:1], 0x2032000
	v_lshl_add_u64 v[4:5], v[0:1], 0, s[0:1]
	s_add_i32 s0, s38, 0x8000
	s_and_b32 s0, s0, 0x8000
	s_add_i32 s29, s59, s0
	s_mov_b32 m0, s29
	s_mov_b64 s[0:1], 0x203a000
	global_load_lds_dwordx4 v[4:5], off
	v_lshl_add_u64 v[4:5], v[0:1], 0, s[0:1]
	s_add_i32 m0, s29, 0x2000
	s_mov_b64 s[0:1], 0x2042000
	global_load_lds_dwordx4 v[4:5], off
	v_lshl_add_u64 v[4:5], v[0:1], 0, s[0:1]
	s_add_i32 m0, s29, 0x4000
	s_mov_b64 s[0:1], 0x204a000
	global_load_lds_dwordx4 v[4:5], off
	v_lshl_add_u64 v[0:1], v[0:1], 0, s[0:1]
	s_add_i32 m0, s29, 0x6000
	s_mov_b32 s0, 0xc074000
	global_load_lds_dwordx4 v[0:1], off
	v_lshl_add_u64 v[250:251], v[168:169], 0, s[64:65]
	v_lshl_add_u64 v[250:251], v[250:251], 0, v[252:253]
	s_mov_b64 s[0:1], 0x2032000
	v_lshl_add_u64 v[4:5], v[250:251], 0, s[0:1]
	s_add_i32 m0, s29, 0xfffff000
	s_mov_b64 s[0:1], 0x203a000
	global_load_lds_dwordx4 v[4:5], off
	v_lshl_add_u64 v[4:5], v[250:251], 0, s[0:1]
	s_add_i32 m0, s29, 0x1000
	s_mov_b64 s[0:1], 0x2042000
	global_load_lds_dwordx4 v[4:5], off
	v_lshl_add_u64 v[4:5], v[250:251], 0, s[0:1]
	s_add_i32 m0, s29, 0x3000
	s_mov_b64 s[0:1], 0x204a000
	global_load_lds_dwordx4 v[4:5], off
	v_lshl_add_u64 v[4:5], v[250:251], 0, s[0:1]
	s_add_i32 m0, s29, 0x5000
	s_mov_b32 s0, 0xc074000
	global_load_lds_dwordx4 v[4:5], off
	v_lshl_add_u64 v[0:1], v[170:171], 0, s[38:39]
	v_add_co_u32_e32 v4, vcc, s0, v0
	s_nop 1
	v_addc_co_u32_e32 v5, vcc, 0, v1, vcc
	v_add_co_u32_e32 v0, vcc, 0xc075000, v0
	global_load_dwordx4 v[98:101], v[4:5], off
	global_load_dwordx4 v[90:93], v[4:5], off offset:1024
	global_load_dwordx4 v[82:85], v[4:5], off offset:2048
	global_load_dwordx4 v[78:81], v[4:5], off offset:3072
	v_addc_co_u32_e32 v1, vcc, 0, v1, vcc
	global_load_dwordx4 v[106:109], v[0:1], off
	global_load_dwordx4 v[102:105], v[0:1], off offset:1024
	global_load_dwordx4 v[94:97], v[0:1], off offset:2048
	global_load_dwordx4 v[86:89], v[0:1], off offset:3072
	s_and_b64 vcc, exec, s[26:27]
	s_cbranch_vccnz .LBB0_1501
	v_lshl_add_u64 v[0:1], v[174:175], 0, s[64:65]
	v_add_co_u32_e32 v0, vcc, 0xa07a000, v0
	s_nop 1
	v_addc_co_u32_e32 v1, vcc, 0, v1, vcc
	global_load_dwordx4 v[6:9], v[0:1], off
	s_branch .LBB0_1501

; #define MLK_ISSUE(chunk_off_elems, buf) do { const char* kg_ = (const char*)(k + (chunk_off_elems)); _Pragma("unroll") for (int i_ = 0; i_ < 4; ++i_) \
;             __builtin_amdgcn_global_load_lds((const unsigned*)(kg_ + kvoff + (size_t)i_ * 16 * DM * 2), (LAS unsigned*)(shm + (buf) * 32768 + (i_ * 8 + wid) * 1024), 16, 0, 0); } while (0)
; template <int SKIP>
; DEV void mlstm_phase(LAS char* shm, const bf16_t* q, const bf16_t* k, const bf16_t* v, const float* gpart, const float* b_ig, const float* b_fg, bf16_t* hc, const bool pre) {
;     ...
;             if (j + 1 < SEQ / CHUNK) {
;                 const size_t cn = cb + (size_t)CHUNK * DM;
;                 MLK_ISSUE(cn, (j + 1) & 1);
; #pragma unroll
;                 for (int ks = 0; ks < 8; ++ks) qnx[ks] = *(const bf16x8*)(qfb + (size_t)(j + 1) * 16384 + ks * 512);
;                 if (wid < 4) vv = *(const uint4*)(v + cn + (size_t)(tid >> 2) * DM + vs * 32 + (tid & 3) * 8);
;             }
;             asm volatile("s_waitcnt lgkmcnt(0)\n\ts_barrier" ::: "memory");
.LBB0_1501:
	s_waitcnt lgkmcnt(0)
	s_barrier
	s_and_b64 vcc, exec, s[70:71]
	s_cbranch_vccnz .Lpf1_done
	s_cmpk_eq_i32 s40, 0xff00
	s_cbranch_scc1 .Lpf1_skip
	s_mov_b32 s0, 0xc074000
	v_lshl_add_u64 v[0:1], v[170:171], 0, s[38:39]
	v_add_co_u32_e32 v4, vcc, s0, v0
	s_nop 1
	v_addc_co_u32_e32 v5, vcc, 0, v1, vcc
	v_add_co_u32_e32 v0, vcc, 0xc075000, v0
	global_load_dwordx4 v[98:101], v[4:5], off
	global_load_dwordx4 v[90:93], v[4:5], off offset:1024
	global_load_dwordx4 v[82:85], v[4:5], off offset:2048
	global_load_dwordx4 v[78:81], v[4:5], off offset:3072
	v_addc_co_u32_e32 v1, vcc, 0, v1, vcc
	global_load_dwordx4 v[106:109], v[0:1], off
	global_load_dwordx4 v[102:105], v[0:1], off offset:1024
	global_load_dwordx4 v[94:97], v[0:1], off offset:2048
	global_load_dwordx4 v[86:89], v[0:1], off offset:3072
	v_lshl_add_u64 v[0:1], v[174:175], 0, s[64:65]
	v_add_co_u32_e32 v0, vcc, 0xa07a000, v0
	s_nop 1
	v_addc_co_u32_e32 v1, vcc, 0, v1, vcc
	global_load_dwordx4 v[6:9], v[0:1], off
